# load ladders de-serialised: DFT stage-1 staging, phase-0 x->bf16 row loop, final RMSNorm loop (gain loads hoisted) on top of attention staging/Q-preload, saddr, no-setprio, barrier realignment
# speedup vs baseline: 1.0054x; 1.0054x over previous
; __device__ __forceinline__ u32x2 pack4(float a, float b, float c, float d) { u32x2 o; o[0] = cvt_pk_bf16(a, b); o[1] = cvt_pk_bf16(c, d); return o; }
; __global__ void __launch_bounds__(512, 2) mega(Params p) {
;     ...
;   for (int r = blockIdx.x * 8 + wv; r < T_TOK; r += G * 8) {
;     const float* src = r < 16384 ? p.in[0] + (size_t)r * DM : p.in[1] + (size_t)(r - 16384) * DM;
;     float ss = 0.f;
; #pragma unroll
;     for (int k = 0; k < 4; ++k) { const f32x4 v = *(const f32x4*)(src + k * 256 + lane * 4);
;       const u32x2 hi = pack4(v[0], v[1], v[2], v[3]);
;       *(u32x2*)(XB + (size_t)r * DM + k * 256 + lane * 4) = hi;
;       ss += v[0] * v[0] + v[1] * v[1] + v[2] * v[2] + v[3] * v[3]; }
; #pragma unroll
;     for (int o = 32; o; o >>= 1) ss += __shfl_xor(ss, o);
;     if (lane < 16) RSS[(size_t)r * 16 + lane] = lane == 0 ? ss : 0.f;
;   }
.LBB0_22:
	s_or_b64 exec, exec, s[18:19]
	v_lshl_add_u64 v[20:21], v[20:21], 0, v[14:15]
	global_load_dwordx4 v[30:33], v[20:21], off
	global_load_dwordx4 v[34:37], v[20:21], off offset:1024
	global_load_dwordx4 v[38:41], v[20:21], off offset:2048
	global_load_dwordx4 v[42:45], v[20:21], off offset:3072
	v_lshlrev_b64 v[48:49], 11, v[18:19]
	v_lshl_add_u64 v[46:47], v[8:9], 0, v[48:49]
	s_waitcnt vmcnt(3)
	v_cvt_pk_bf16_f32 v48, v30, v31
	v_cvt_pk_bf16_f32 v49, v32, v33
	global_store_dwordx2 v[46:47], v[48:49], off
	v_mul_f32_e32 v6, v31, v31
	v_fmac_f32_e32 v6, v30, v30
	v_fmac_f32_e32 v6, v32, v32
	v_fmac_f32_e32 v6, v33, v33
	s_waitcnt vmcnt(3)
	v_cvt_pk_bf16_f32 v50, v34, v35
	v_cvt_pk_bf16_f32 v51, v36, v37
	global_store_dwordx2 v[46:47], v[50:51], off offset:512
	s_waitcnt vmcnt(3)
	v_cvt_pk_bf16_f32 v52, v38, v39
	v_cvt_pk_bf16_f32 v53, v40, v41
	global_store_dwordx2 v[46:47], v[52:53], off offset:1024
	v_mul_f32_e32 v20, v35, v35
	v_fmac_f32_e32 v20, v34, v34
	v_fmac_f32_e32 v20, v36, v36
	v_fmac_f32_e32 v20, v37, v37
	v_add_f32_e32 v6, v6, v20
	v_mul_f32_e32 v20, v39, v39
	v_fmac_f32_e32 v20, v38, v38
	v_fmac_f32_e32 v20, v40, v40
	v_fmac_f32_e32 v20, v41, v41
	v_add_f32_e32 v6, v6, v20
	s_waitcnt vmcnt(3)
	v_mul_f32_e32 v20, v43, v43
	v_fmac_f32_e32 v20, v42, v42
	v_fmac_f32_e32 v20, v44, v44
	v_fmac_f32_e32 v20, v45, v45
	v_add_f32_e32 v6, v6, v20
	ds_bpermute_b32 v20, v3, v6
	v_cvt_pk_bf16_f32 v54, v42, v43
	v_cvt_pk_bf16_f32 v55, v44, v45
	global_store_dwordx2 v[46:47], v[54:55], off offset:1536
	s_waitcnt lgkmcnt(0)
	v_add_f32_e32 v6, v6, v20
	ds_bpermute_b32 v20, v5, v6
	s_waitcnt lgkmcnt(0)
	v_add_f32_e32 v6, v6, v20
	ds_bpermute_b32 v20, v25, v6
	s_waitcnt lgkmcnt(0)
	v_add_f32_e32 v6, v6, v20
	ds_bpermute_b32 v20, v26, v6
	s_waitcnt lgkmcnt(0)
	v_add_f32_e32 v6, v6, v20
	ds_bpermute_b32 v20, v27, v6
	s_waitcnt lgkmcnt(0)
	v_add_f32_e32 v6, v6, v20
	ds_bpermute_b32 v20, v28, v6
	s_and_saveexec_b64 s[6:7], vcc
	s_cbranch_execz .LBB0_19
	s_waitcnt lgkmcnt(0)
	v_add_f32_e32 v6, v6, v20
	v_lshlrev_b64 v[18:19], 6, v[18:19]
	v_lshl_add_u64 v[18:19], v[10:11], 0, v[18:19]
	v_cndmask_b32_e64 v6, 0, v6, s[4:5]
	global_store_dword v[18:19], v6, off
	s_branch .LBB0_19

; #define LAS __attribute__((address_space(3)))
; __device__ __forceinline__ f32x16 mfma32(bf16x8 a, bf16x8 b, f32x16 c) { return __builtin_amdgcn_mfma_f32_32x32x16_bf16(a, b, c, 0, 0, 0); }
; template <int STAGE>
; __device__ void dft_item(const bf16_t* __restrict__ src, bf16_t* __restrict__ dst, const bf16_t* __restrict__ Ct, const bf16_t* __restrict__ St,
;                          int N, int lgN, int rowbase, int j, int chblk, int S, int N1, int N2, LAS unsigned char* lds) {
;     ...
; #pragma unroll
;   for (int it = 0; it < 4; ++it) {
;     const int q = tid + it * 512, n = q >> lgcpr, cq = q & (cpr - 1), part = cq >> (lgcpr - 1), cc = cq & ((cpr >> 1) - 1);
;     const int irow = STAGE == 1 ? rowbase + N2 * n + j : rowbase + j * N2 + n;
;     const u32x4 v = *(const u32x4*)(src + (size_t)irow * 1024 + part * 512 + chblk * CB + cc * 8);
;     *(LAS u32x4*)(lds + n * stride + (part * CB + cc * 8) * 2) = v;
;   }
;   __syncthreads();
;   const int kts = N >> 5, kt = w & (kts - 1), chsub = w >> (lgN - 5);
;   const int i16 = l & 15, q4 = i16 >> 2, p4 = i16 & 3, G1 = (l >> 4) & 1, h = l >> 5;
;   const unsigned colre = (unsigned)(chsub * 32 + 16 * G1 + 4 * p4) * 2u, colim = colre + (unsigned)CB * 2u;
;   const int kout = kt * 32 + (l & 31);
;   f32x16 a0 = {}, a1 = {}, a2 = {};
;   const int nks = N >> 4;
;   bf16x8 Bc[8], Bs[8];
; #pragma unroll
;   for (int ks = 0; ks < 8; ++ks) if (ks < nks) { Bc[ks] = *(const bf16x8*)(Ct + kout * N + 16 * ks + 8 * h); Bs[ks] = *(const bf16x8*)(St + kout * N + 16 * ks + 8 * h); }
; #pragma unroll
;   for (int ks = 0; ks < 8; ++ks) if (ks < nks) {
;     const unsigned rlo = (unsigned)(16 * ks + 8 * h + q4) * stride, rhi = rlo + 4u * stride;
;     const bf16x8 Ar = tr_frag(lds, rlo + colre, rhi + colre), Ai = tr_frag(lds, rlo + colim, rhi + colim);
;     a0 = mfma32(Ar, Bc[ks], a0); a0 = mfma32(Ai, Bs[ks], a0);
;     if (STAGE == 1) { a1 = mfma32(Ai, Bc[ks], a1); a2 = mfma32(Ar, Bs[ks], a2); }
;   }
.LBB0_433:
	s_cmpk_gt_i32 s13, 0x3ff
	s_mov_b64 s[22:23], -1
	s_cbranch_scc0 .LBB0_435
	s_and_b32 s20, s12, 0x7ffff800
	s_bfe_u32 s34, s13, 0x60001
	s_or_b32 s23, s20, s34
	v_mov_b32_e32 v6, v214
	s_addk_i32 s23, 0xc000
	v_and_b32_e32 v0, 0xffffffc0, v6
	v_add_u32_e32 v0, s23, v0
	v_ashrrev_i32_e32 v1, 31, v0
	v_lshlrev_b32_e32 v2, 4, v6
	v_lshlrev_b64 v[0:1], 11, v[0:1]
	v_and_b32_e32 v8, 0x200, v2
	s_and_b32 s22, s7, 0x100
	v_lshl_add_u64 v[0:1], s[4:5], 0, v[0:1]
	v_lshlrev_b32_e32 v160, 1, v8
	v_lshl_add_u64 v[0:1], v[0:1], 0, v[160:161]
	s_lshl_b32 s20, s22, 1
	v_lshl_add_u64 v[0:1], v[0:1], 0, s[20:21]
	v_and_b32_e32 v4, 0x1f0, v2
	v_mov_b32_e32 v5, v161
	v_lshl_add_u64 v[0:1], v[0:1], 0, v[4:5]
	global_load_dwordx4 v[12:15], v[0:1], off
	v_ashrrev_i32_e32 v7, 6, v6
	s_movk_i32 s35, 0x440
	v_mul_lo_u32 v9, v7, s35
	v_add_u32_e32 v9, 0, v9
	v_add3_u32 v9, v9, v8, v4
	v_and_b32_e32 v59, 31, v6
	v_readlane_b32 s36, v252, 33
	v_lshlrev_b32_e32 v58, 5, v7
	v_readlane_b32 s37, v252, 34
	v_mov_b32_e32 v57, v161
	v_mov_b32_e32 v28, v9
	v_add_u32_e32 v0, 0x200, v6
	v_lshrrev_b32_e32 v9, 6, v0
	v_and_b32_e32 v0, 0xffffffc0, v0
	v_add_u32_e32 v0, s23, v0
	v_ashrrev_i32_e32 v1, 31, v0
	v_lshlrev_b64 v[0:1], 11, v[0:1]
	v_lshl_add_u64 v[0:1], s[4:5], 0, v[0:1]
	v_lshl_add_u64 v[0:1], v[0:1], 0, v[160:161]
	v_lshl_add_u64 v[0:1], v[0:1], 0, s[20:21]
	v_lshl_add_u64 v[0:1], v[0:1], 0, v[4:5]
	global_load_dwordx4 v[16:19], v[0:1], off
	v_mul_lo_u32 v9, v9, s35
	v_add_u32_e32 v9, 0, v9
	v_add3_u32 v9, v9, v8, v4
	v_mov_b32_e32 v29, v9
	v_add_u32_e32 v0, 0x400, v6
	v_lshrrev_b32_e32 v9, 6, v0
	v_and_b32_e32 v0, 0xffffffc0, v0
	v_add_u32_e32 v0, s23, v0
	v_ashrrev_i32_e32 v1, 31, v0
	v_lshlrev_b64 v[0:1], 11, v[0:1]
	v_lshl_add_u64 v[0:1], s[4:5], 0, v[0:1]
	v_lshl_add_u64 v[0:1], v[0:1], 0, v[160:161]
	v_lshl_add_u64 v[0:1], v[0:1], 0, s[20:21]
	v_lshl_add_u64 v[0:1], v[0:1], 0, v[4:5]
	global_load_dwordx4 v[20:23], v[0:1], off
	v_mul_lo_u32 v9, v9, s35
	v_add_u32_e32 v9, 0, v9
	v_add3_u32 v9, v9, v8, v4
	v_mov_b32_e32 v30, v9
	v_add_u32_e32 v0, 0x600, v6
	v_lshrrev_b32_e32 v9, 6, v0
	v_and_b32_e32 v0, 0xffffffc0, v0
	v_add_u32_e32 v0, s23, v0
	v_ashrrev_i32_e32 v1, 31, v0
	v_lshlrev_b64 v[0:1], 11, v[0:1]
	v_lshl_add_u64 v[0:1], s[4:5], 0, v[0:1]
	v_lshl_add_u64 v[0:1], v[0:1], 0, v[160:161]
	v_lshl_add_u64 v[0:1], v[0:1], 0, s[20:21]
	v_lshl_add_u64 v[0:1], v[0:1], 0, v[4:5]
	global_load_dwordx4 v[24:27], v[0:1], off
	v_mul_lo_u32 v5, v9, s35
	v_add_u32_e32 v5, 0, v5
	v_add3_u32 v4, v5, v8, v4
	v_lshlrev_b32_e32 v160, 6, v59
	v_mul_u32_u24_e32 v59, s34, v59
	v_cvt_f32_u32_e32 v59, v59
	v_mul_f32_e32 v59, 0x3a000000, v59
	v_mov_b32_e32 v31, v4
	s_waitcnt vmcnt(3)
	ds_write_b128 v28, v[12:15]
	s_waitcnt vmcnt(2)
	ds_write_b128 v29, v[16:19]
	s_waitcnt vmcnt(1)
	ds_write_b128 v30, v[20:23]
	s_waitcnt vmcnt(0)
	ds_write_b128 v31, v[24:27]
	v_lshlrev_b32_e32 v1, 2, v6
	v_and_b32_e32 v0, 16, v6
	v_and_b32_e32 v1, 12, v1
	v_or3_b32 v5, v0, v1, v58
	v_lshl_add_u64 v[0:1], s[36:37], 0, v[160:161]
	v_lshrrev_b32_e32 v2, 1, v6
	v_readlane_b32 s36, v252, 35
	v_and_b32_e32 v56, 16, v2
	v_readlane_b32 s37, v252, 36
	v_lshl_add_u64 v[0:1], v[0:1], 0, v[56:57]
	s_waitcnt lgkmcnt(0)
	v_lshl_add_u64 v[2:3], s[36:37], 0, v[160:161]
	s_barrier
	v_lshl_add_u64 v[2:3], v[2:3], 0, v[56:57]
	global_load_dwordx4 v[16:19], v[0:1], off
	global_load_dwordx4 v[32:35], v[2:3], off
	global_load_dwordx4 v[60:63], v[0:1], off offset:32
	global_load_dwordx4 v[64:67], v[2:3], off offset:32
	v_lshrrev_b32_e32 v4, 2, v6
	v_and_b32_e32 v1, 11, v4
	v_lshlrev_b32_e32 v0, 1, v5
	v_mul_u32_u24_e32 v1, 0x440, v1
	v_add3_u32 v74, 0, v0, v1
	ds_read_b64_tr_b16 v[36:37], v74
	ds_read_b64_tr_b16 v[38:39], v74 offset:4352
	ds_read_b64_tr_b16 v[20:21], v74 offset:512
	ds_read_b64_tr_b16 v[22:23], v74 offset:4864
	ds_read_b64_tr_b16 v[68:69], v74 offset:17408
	ds_read_b64_tr_b16 v[70:71], v74 offset:21760
	ds_read_b64_tr_b16 v[72:73], v74 offset:17920
	ds_read_b64_tr_b16 v[74:75], v74 offset:22272
	v_or_b32_e32 v160, s23, v160
	s_waitcnt vmcnt(3) lgkmcnt(6)
	v_mfma_f32_32x32x16_bf16 v[0:15], v[36:39], v[16:19], 0
	s_waitcnt vmcnt(2) lgkmcnt(4)
	v_mfma_f32_32x32x16_bf16 v[0:15], v[20:23], v[32:35], v[0:15]
	v_mfma_f32_32x32x16_bf16 v[16:31], v[20:23], v[16:19], 0
	v_mfma_f32_32x32x16_bf16 v[32:47], v[36:39], v[32:35], 0
	s_waitcnt vmcnt(1) lgkmcnt(2)
	v_mfma_f32_32x32x16_bf16 v[0:15], v[68:71], v[60:63], v[0:15]
	s_waitcnt vmcnt(0) lgkmcnt(0)
; __device__ __forceinline__ f32x16 mfma32(bf16x8 a, bf16x8 b, f32x16 c) { return __builtin_amdgcn_mfma_f32_32x32x16_bf16(a, b, c, 0, 0, 0); }
; template <int STAGE>
; __device__ void dft_item(const bf16_t* __restrict__ src, bf16_t* __restrict__ dst, const bf16_t* __restrict__ Ct, const bf16_t* __restrict__ St,
;                          int N, int lgN, int rowbase, int j, int chblk, int S, int N1, int N2, LAS unsigned char* lds) {
;     ...
;     a0 = mfma32(Ar, Bc[ks], a0); a0 = mfma32(Ai, Bs[ks], a0);
;     if (STAGE == 1) { a1 = mfma32(Ai, Bc[ks], a1); a2 = mfma32(Ar, Bs[ks], a2); }
;   }
;   const int chb = chblk * CB + chsub * 32;
;   if (STAGE == 1) {
;     const int mm = (j * kout) & (S - 1); const float fr = (float)mm / (float)S;
;     const float c = __builtin_amdgcn_cosf(fr), s = __builtin_amdgcn_sinf(fr);
;     const size_t orow = (size_t)(rowbase + kout * N2 + j) * 1024;
;     f32x16 re, im;
; #pragma unroll
;     for (int i = 0; i < 16; ++i) { const float yr = a0[i], yi = a1[i] - a2[i]; re[i] = yr * c + yi * s; im[i] = yi * c - yr * s; }
;     store_tile16(dst + orow + chb, re, 1.f, h); store_tile16(dst + orow + 512 + chb, im, 1.f, h);
;   } else {
;     const size_t orow = (size_t)(rowbase + j + N1 * kout) * 512;
;     store_tile16(dst + orow + chb, a0, 1.f, h);
;   }
;   __syncthreads();
	v_mfma_f32_32x32x16_bf16 v[0:15], v[72:75], v[64:67], v[0:15]
	v_mfma_f32_32x32x16_bf16 v[16:31], v[72:75], v[60:63], v[16:31]
	v_sin_f32_e32 v62, v59
	v_cos_f32_e32 v60, v59
	v_mfma_f32_32x32x16_bf16 v[32:47], v[68:71], v[64:67], v[32:47]
	s_nop 11
	v_sub_f32_e32 v47, v31, v47
	v_sub_f32_e32 v46, v30, v46
	v_sub_f32_e32 v31, v23, v39
	v_sub_f32_e32 v30, v22, v38
	v_sub_f32_e32 v23, v21, v37
	v_sub_f32_e32 v22, v20, v36
	v_sub_f32_e32 v21, v19, v35
	v_sub_f32_e32 v20, v18, v34
	v_sub_f32_e32 v19, v17, v33
	v_sub_f32_e32 v18, v16, v32
	v_pk_mul_f32 v[16:17], v[62:63], v[0:1] op_sel_hi:[0,1]
	v_pk_fma_f32 v[16:17], v[60:61], v[18:19], v[16:17] op_sel_hi:[0,1,1] neg_lo:[0,0,1] neg_hi:[0,0,1]
	v_pk_mul_f32 v[18:19], v[62:63], v[18:19] op_sel_hi:[0,1]
	v_sub_f32_e32 v41, v25, v41
	v_sub_f32_e32 v40, v24, v40
	v_pk_fma_f32 v[24:25], v[60:61], v[0:1], v[18:19] op_sel_hi:[0,1,1]
	v_pk_mul_f32 v[0:1], v[62:63], v[2:3] op_sel_hi:[0,1]
	v_pk_fma_f32 v[18:19], v[60:61], v[20:21], v[0:1] op_sel_hi:[0,1,1] neg_lo:[0,0,1] neg_hi:[0,0,1]
	v_pk_mul_f32 v[0:1], v[62:63], v[20:21] op_sel_hi:[0,1]
	v_sub_f32_e32 v43, v27, v43
	v_sub_f32_e32 v42, v26, v42
	v_pk_fma_f32 v[26:27], v[60:61], v[2:3], v[0:1] op_sel_hi:[0,1,1]
	v_pk_mul_f32 v[0:1], v[62:63], v[4:5] op_sel_hi:[0,1]
	v_pk_fma_f32 v[20:21], v[60:61], v[22:23], v[0:1] op_sel_hi:[0,1,1] neg_lo:[0,0,1] neg_hi:[0,0,1]
	v_pk_mul_f32 v[0:1], v[62:63], v[22:23] op_sel_hi:[0,1]
	v_sub_f32_e32 v45, v29, v45
	v_sub_f32_e32 v44, v28, v44
	v_pk_fma_f32 v[28:29], v[60:61], v[4:5], v[0:1] op_sel_hi:[0,1,1]
	v_pk_mul_f32 v[0:1], v[62:63], v[6:7] op_sel_hi:[0,1]
	v_pk_fma_f32 v[22:23], v[60:61], v[30:31], v[0:1] op_sel_hi:[0,1,1] neg_lo:[0,0,1] neg_hi:[0,0,1]
	v_pk_mul_f32 v[0:1], v[62:63], v[30:31] op_sel_hi:[0,1]
	v_pk_fma_f32 v[30:31], v[60:61], v[6:7], v[0:1] op_sel_hi:[0,1,1]
	v_pk_mul_f32 v[2:3], v[62:63], v[40:41] op_sel_hi:[0,1]
	v_pk_mul_f32 v[4:5], v[62:63], v[42:43] op_sel_hi:[0,1]
	v_pk_mul_f32 v[6:7], v[62:63], v[44:45] op_sel_hi:[0,1]
	v_pk_mul_f32 v[32:33], v[62:63], v[46:47] op_sel_hi:[0,1]
	v_pk_mul_f32 v[0:1], v[62:63], v[8:9] op_sel_hi:[0,1]
	v_pk_fma_f32 v[8:9], v[60:61], v[8:9], v[2:3] op_sel_hi:[0,1,1]
	v_pk_mul_f32 v[2:3], v[62:63], v[10:11] op_sel_hi:[0,1]
	v_pk_fma_f32 v[10:11], v[60:61], v[10:11], v[4:5] op_sel_hi:[0,1,1]
	v_pk_mul_f32 v[4:5], v[62:63], v[12:13] op_sel_hi:[0,1]
	v_pk_fma_f32 v[12:13], v[60:61], v[12:13], v[6:7] op_sel_hi:[0,1,1]
	v_pk_mul_f32 v[6:7], v[62:63], v[14:15] op_sel_hi:[0,1]
	v_pk_fma_f32 v[14:15], v[60:61], v[14:15], v[32:33] op_sel_hi:[0,1,1]
	v_add_u32_e32 v32, s22, v58
	v_lshlrev_b64 v[34:35], 11, v[160:161]
	v_lshl_add_u64 v[34:35], s[10:11], 0, v[34:35]
	v_ashrrev_i32_e32 v33, 31, v32
	v_lshl_add_u64 v[32:33], v[32:33], 1, v[34:35]
	v_cvt_pk_bf16_f32 v8, v8, v9
	v_cvt_pk_bf16_f32 v9, v10, v11
	v_cvt_pk_bf16_f32 v10, v12, v13
	v_cvt_pk_bf16_f32 v11, v14, v15
	v_pk_fma_f32 v[0:1], v[60:61], v[40:41], v[0:1] op_sel_hi:[0,1,1] neg_lo:[0,0,1] neg_hi:[0,0,1]
	v_pk_fma_f32 v[2:3], v[60:61], v[42:43], v[2:3] op_sel_hi:[0,1,1] neg_lo:[0,0,1] neg_hi:[0,0,1]
	v_pk_fma_f32 v[4:5], v[60:61], v[44:45], v[4:5] op_sel_hi:[0,1,1] neg_lo:[0,0,1] neg_hi:[0,0,1]
	v_pk_fma_f32 v[6:7], v[60:61], v[46:47], v[6:7] op_sel_hi:[0,1,1] neg_lo:[0,0,1] neg_hi:[0,0,1]
	v_lshl_add_u64 v[32:33], v[32:33], 0, v[56:57]
	v_permlane32_swap_b32_e32 v8, v10
	v_permlane32_swap_b32_e32 v9, v11
	v_cvt_pk_bf16_f32 v24, v24, v25
	v_cvt_pk_bf16_f32 v25, v26, v27
	v_cvt_pk_bf16_f32 v26, v28, v29
	v_cvt_pk_bf16_f32 v27, v30, v31
	global_store_dwordx4 v[32:33], v[8:11], off offset:32
	v_cvt_pk_bf16_f32 v0, v0, v1
	v_cvt_pk_bf16_f32 v1, v2, v3
	v_cvt_pk_bf16_f32 v8, v16, v17
	v_cvt_pk_bf16_f32 v9, v18, v19
	v_cvt_pk_bf16_f32 v10, v20, v21
	v_cvt_pk_bf16_f32 v11, v22, v23
	v_cvt_pk_bf16_f32 v2, v4, v5
	v_cvt_pk_bf16_f32 v3, v6, v7
	v_permlane32_swap_b32_e32 v24, v26
	v_permlane32_swap_b32_e32 v25, v27
	v_permlane32_swap_b32_e32 v8, v10
	v_permlane32_swap_b32_e32 v9, v11
	v_permlane32_swap_b32_e32 v0, v2
	v_permlane32_swap_b32_e32 v1, v3
	global_store_dwordx4 v[32:33], v[24:27], off
	global_store_dwordx4 v[32:33], v[8:11], off offset:1024
	global_store_dwordx4 v[32:33], v[0:3], off offset:1056
	s_barrier
	s_mov_b64 s[22:23], 0
; #define LAS __attribute__((address_space(3)))
; __device__ __forceinline__ f32x16 mfma32(bf16x8 a, bf16x8 b, f32x16 c) { return __builtin_amdgcn_mfma_f32_32x32x16_bf16(a, b, c, 0, 0, 0); }
; template <int STAGE>
; __device__ void dft_item(const bf16_t* __restrict__ src, bf16_t* __restrict__ dst, const bf16_t* __restrict__ Ct, const bf16_t* __restrict__ St,
;                          int N, int lgN, int rowbase, int j, int chblk, int S, int N1, int N2, LAS unsigned char* lds) {
;     ...
; #pragma unroll
;   for (int it = 0; it < 4; ++it) {
;     const int q = tid + it * 512, n = q >> lgcpr, cq = q & (cpr - 1), part = cq >> (lgcpr - 1), cc = cq & ((cpr >> 1) - 1);
;     const int irow = STAGE == 1 ? rowbase + N2 * n + j : rowbase + j * N2 + n;
;     const u32x4 v = *(const u32x4*)(src + (size_t)irow * 1024 + part * 512 + chblk * CB + cc * 8);
;     *(LAS u32x4*)(lds + n * stride + (part * CB + cc * 8) * 2) = v;
;   }
;   __syncthreads();
;   const int kts = N >> 5, kt = w & (kts - 1), chsub = w >> (lgN - 5);
;   const int i16 = l & 15, q4 = i16 >> 2, p4 = i16 & 3, G1 = (l >> 4) & 1, h = l >> 5;
;   const unsigned colre = (unsigned)(chsub * 32 + 16 * G1 + 4 * p4) * 2u, colim = colre + (unsigned)CB * 2u;
;   const int kout = kt * 32 + (l & 31);
;   f32x16 a0 = {}, a1 = {}, a2 = {};
;   const int nks = N >> 4;
;   bf16x8 Bc[8], Bs[8];
; #pragma unroll
;   for (int ks = 0; ks < 8; ++ks) if (ks < nks) { Bc[ks] = *(const bf16x8*)(Ct + kout * N + 16 * ks + 8 * h); Bs[ks] = *(const bf16x8*)(St + kout * N + 16 * ks + 8 * h); }
; #pragma unroll
;   for (int ks = 0; ks < 8; ++ks) if (ks < nks) {
;     const unsigned rlo = (unsigned)(16 * ks + 8 * h + q4) * stride, rhi = rlo + 4u * stride;
;     const bf16x8 Ar = tr_frag(lds, rlo + colre, rhi + colre), Ai = tr_frag(lds, rlo + colim, rhi + colim);
;     a0 = mfma32(Ar, Bc[ks], a0); a0 = mfma32(Ai, Bs[ks], a0);
;     if (STAGE == 1) { a1 = mfma32(Ai, Bc[ks], a1); a2 = mfma32(Ar, Bs[ks], a2); }
;   }
.LBB0_435:
	s_andn2_b64 vcc, exec, s[22:23]
	s_cbranch_vccnz .LBB0_432
	s_ashr_i32 s34, s13, 3
	v_mov_b32_e32 v6, v214
	s_add_i32 s23, s34, 0x4000
	v_ashrrev_i32_e32 v7, 4, v6
	v_lshl_add_u32 v0, v7, 7, s23
	v_ashrrev_i32_e32 v1, 31, v0
	v_bfe_u32 v8, v6, 3, 1
	v_lshlrev_b64 v[0:1], 11, v[0:1]
	s_and_b32 s22, s6, 0x1c0
	v_lshl_add_u64 v[0:1], s[4:5], 0, v[0:1]
	v_lshlrev_b32_e32 v160, 10, v8
	v_lshl_add_u64 v[0:1], v[0:1], 0, v[160:161]
	s_lshl_b32 s20, s22, 1
	v_lshlrev_b32_e32 v2, 4, v6
	v_lshl_add_u64 v[0:1], v[0:1], 0, s[20:21]
	v_and_b32_e32 v4, 0x70, v2
	v_mov_b32_e32 v5, v161
	v_lshl_add_u64 v[0:1], v[0:1], 0, v[4:5]
	global_load_dwordx4 v[12:15], v[0:1], off
	s_movk_i32 s35, 0x140
	v_mul_lo_u32 v7, v7, s35
	v_add_u32_e32 v7, 0, v7
	v_lshlrev_b32_e32 v8, 7, v8
	v_add3_u32 v7, v7, v8, v4
	v_readlane_b32 s36, v250, 49
	v_readlane_b32 s37, v250, 50
	v_mov_b32_e32 v105, v161
	v_mov_b32_e32 v28, v7
	v_add_u32_e32 v0, 0x200, v6
	v_ashrrev_i32_e32 v7, 4, v0
	v_lshl_add_u32 v0, v7, 7, s23
	v_ashrrev_i32_e32 v1, 31, v0
	v_lshlrev_b64 v[0:1], 11, v[0:1]
	v_lshl_add_u64 v[0:1], s[4:5], 0, v[0:1]
	v_lshl_add_u64 v[0:1], v[0:1], 0, v[160:161]
	v_lshl_add_u64 v[0:1], v[0:1], 0, s[20:21]
	v_lshl_add_u64 v[0:1], v[0:1], 0, v[4:5]
	global_load_dwordx4 v[16:19], v[0:1], off
	v_mul_lo_u32 v7, v7, s35
	v_add_u32_e32 v7, 0, v7
	v_add3_u32 v7, v7, v8, v4
	v_mov_b32_e32 v29, v7
	v_add_u32_e32 v0, 0x400, v6
	v_ashrrev_i32_e32 v7, 4, v0
	v_lshl_add_u32 v0, v7, 7, s23
	v_ashrrev_i32_e32 v1, 31, v0
	v_lshlrev_b64 v[0:1], 11, v[0:1]
	v_lshl_add_u64 v[0:1], s[4:5], 0, v[0:1]
	v_lshl_add_u64 v[0:1], v[0:1], 0, v[160:161]
	v_lshl_add_u64 v[0:1], v[0:1], 0, s[20:21]
	v_lshl_add_u64 v[0:1], v[0:1], 0, v[4:5]
	global_load_dwordx4 v[20:23], v[0:1], off
	v_mul_lo_u32 v7, v7, s35
	v_add_u32_e32 v7, 0, v7
	v_add3_u32 v7, v7, v8, v4
	v_mov_b32_e32 v30, v7
	v_add_u32_e32 v0, 0x600, v6
	v_ashrrev_i32_e32 v7, 4, v0
	v_lshl_add_u32 v0, v7, 7, s23
	v_ashrrev_i32_e32 v1, 31, v0
	v_lshlrev_b64 v[0:1], 11, v[0:1]
	v_lshl_add_u64 v[0:1], s[4:5], 0, v[0:1]
	v_lshl_add_u64 v[0:1], v[0:1], 0, v[160:161]
	v_lshl_add_u64 v[0:1], v[0:1], 0, s[20:21]
	v_lshl_add_u64 v[0:1], v[0:1], 0, v[4:5]
	global_load_dwordx4 v[24:27], v[0:1], off
	v_mul_lo_u32 v5, v7, s35
	v_add_u32_e32 v5, 0, v5
	v_add3_u32 v4, v5, v8, v4
	v_mov_b32_e32 v31, v4
	s_waitcnt vmcnt(3)
	ds_write_b128 v28, v[12:15]
	s_waitcnt vmcnt(2)
	ds_write_b128 v29, v[16:19]
	s_waitcnt vmcnt(1)
	ds_write_b128 v30, v[20:23]
	s_waitcnt vmcnt(0)
	ds_write_b128 v31, v[24:27]
	v_ashrrev_i32_e32 v1, 3, v6
	v_and_b32_e32 v106, 0xffffffe0, v1
	v_lshlrev_b32_e32 v1, 2, v6
	v_and_b32_e32 v0, 16, v6
	v_and_b32_e32 v1, 12, v1
	v_or3_b32 v5, v0, v1, v106
	v_lshrrev_b32_e32 v2, 1, v6
	v_and_b32_e32 v0, 31, v6
	v_and_or_b32 v107, v2, s77, v0
	v_lshlrev_b32_e32 v160, 8, v107
	v_lshl_add_u64 v[0:1], s[36:37], 0, v[160:161]
	v_readlane_b32 s36, v252, 37
	v_and_b32_e32 v104, 16, v2
	v_readlane_b32 s37, v252, 38
	v_lshl_add_u64 v[0:1], v[0:1], 0, v[104:105]
	s_waitcnt lgkmcnt(0)
	v_lshl_add_u64 v[2:3], s[36:37], 0, v[160:161]
	s_barrier
	v_lshl_add_u64 v[2:3], v[2:3], 0, v[104:105]
	global_load_dwordx4 v[16:19], v[0:1], off
	global_load_dwordx4 v[32:35], v[2:3], off
	global_load_dwordx4 v[108:111], v[0:1], off offset:32
	global_load_dwordx4 v[112:115], v[2:3], off offset:32
	global_load_dwordx4 v[100:103], v[0:1], off offset:64
	global_load_dwordx4 v[96:99], v[2:3], off offset:64
	global_load_dwordx4 v[92:95], v[0:1], off offset:96
	global_load_dwordx4 v[88:91], v[2:3], off offset:96
	global_load_dwordx4 v[84:87], v[0:1], off offset:128
	global_load_dwordx4 v[80:83], v[2:3], off offset:128
	global_load_dwordx4 v[76:79], v[0:1], off offset:160
	global_load_dwordx4 v[72:75], v[2:3], off offset:160
	global_load_dwordx4 v[68:71], v[0:1], off offset:192
	global_load_dwordx4 v[64:67], v[2:3], off offset:192
	global_load_dwordx4 v[60:63], v[0:1], off offset:224
	global_load_dwordx4 v[56:59], v[2:3], off offset:224
	v_lshrrev_b32_e32 v4, 2, v6
	v_and_b32_e32 v1, 11, v4
	v_lshlrev_b32_e32 v0, 1, v5
	v_mul_u32_u24_e32 v1, 0x140, v1
	v_add3_u32 v124, 0, v0, v1
	ds_read_b64_tr_b16 v[36:37], v124
	ds_read_b64_tr_b16 v[38:39], v124 offset:1280
	ds_read_b64_tr_b16 v[20:21], v124 offset:128
	ds_read_b64_tr_b16 v[22:23], v124 offset:1408
	ds_read_b64_tr_b16 v[116:117], v124 offset:5120
	ds_read_b64_tr_b16 v[118:119], v124 offset:6400
	ds_read_b64_tr_b16 v[120:121], v124 offset:5248
	ds_read_b64_tr_b16 v[122:123], v124 offset:6528
	s_waitcnt vmcnt(15) lgkmcnt(6)
	v_mfma_f32_32x32x16_bf16 v[0:15], v[36:39], v[16:19], 0
	s_waitcnt vmcnt(14) lgkmcnt(4)
	v_mfma_f32_32x32x16_bf16 v[0:15], v[20:23], v[32:35], v[0:15]
	s_waitcnt vmcnt(13) lgkmcnt(2)
	v_mfma_f32_32x32x16_bf16 v[0:15], v[116:119], v[108:111], v[0:15]
	v_mfma_f32_32x32x16_bf16 v[16:31], v[20:23], v[16:19], 0
	v_mfma_f32_32x32x16_bf16 v[32:47], v[36:39], v[32:35], 0
	s_waitcnt vmcnt(12) lgkmcnt(0)
	v_mfma_f32_32x32x16_bf16 v[0:15], v[120:123], v[112:115], v[0:15]
	v_mfma_f32_32x32x16_bf16 v[16:31], v[120:123], v[108:111], v[16:31]
	v_mfma_f32_32x32x16_bf16 v[32:47], v[116:119], v[112:115], v[32:47]
	ds_read_b64_tr_b16 v[108:109], v124 offset:10240
	ds_read_b64_tr_b16 v[110:111], v124 offset:11520
	ds_read_b64_tr_b16 v[112:113], v124 offset:10368
	ds_read_b64_tr_b16 v[114:115], v124 offset:11648
	s_waitcnt vmcnt(11) lgkmcnt(2)
	v_mfma_f32_32x32x16_bf16 v[0:15], v[108:111], v[100:103], v[0:15]
	s_waitcnt vmcnt(10) lgkmcnt(0)
; __device__ __forceinline__ f32x16 mfma32(bf16x8 a, bf16x8 b, f32x16 c) { return __builtin_amdgcn_mfma_f32_32x32x16_bf16(a, b, c, 0, 0, 0); }
; template <int STAGE>
; __device__ void dft_item(const bf16_t* __restrict__ src, bf16_t* __restrict__ dst, const bf16_t* __restrict__ Ct, const bf16_t* __restrict__ St,
;                          int N, int lgN, int rowbase, int j, int chblk, int S, int N1, int N2, LAS unsigned char* lds) {
;     ...
; #pragma unroll
;   for (int ks = 0; ks < 8; ++ks) if (ks < nks) {
;     const unsigned rlo = (unsigned)(16 * ks + 8 * h + q4) * stride, rhi = rlo + 4u * stride;
;     const bf16x8 Ar = tr_frag(lds, rlo + colre, rhi + colre), Ai = tr_frag(lds, rlo + colim, rhi + colim);
;     a0 = mfma32(Ar, Bc[ks], a0); a0 = mfma32(Ai, Bs[ks], a0);
;     if (STAGE == 1) { a1 = mfma32(Ai, Bc[ks], a1); a2 = mfma32(Ar, Bs[ks], a2); }
;   }
;   const int chb = chblk * CB + chsub * 32;
;   if (STAGE == 1) {
;     const int mm = (j * kout) & (S - 1); const float fr = (float)mm / (float)S;
;     const float c = __builtin_amdgcn_cosf(fr), s = __builtin_amdgcn_sinf(fr);
;     const size_t orow = (size_t)(rowbase + kout * N2 + j) * 1024;
;     f32x16 re, im;
; #pragma unroll
;     for (int i = 0; i < 16; ++i) { const float yr = a0[i], yi = a1[i] - a2[i]; re[i] = yr * c + yi * s; im[i] = yi * c - yr * s; }
;     store_tile16(dst + orow + chb, re, 1.f, h); store_tile16(dst + orow + 512 + chb, im, 1.f, h);
;   } else {
;     const size_t orow = (size_t)(rowbase + j + N1 * kout) * 512;
;     store_tile16(dst + orow + chb, a0, 1.f, h);
;   }
;   __syncthreads();
	v_mfma_f32_32x32x16_bf16 v[0:15], v[112:115], v[96:99], v[0:15]
	v_mfma_f32_32x32x16_bf16 v[16:31], v[112:115], v[100:103], v[16:31]
	v_mfma_f32_32x32x16_bf16 v[32:47], v[108:111], v[96:99], v[32:47]
	ds_read_b64_tr_b16 v[96:97], v124 offset:15360
	ds_read_b64_tr_b16 v[98:99], v124 offset:16640
	ds_read_b64_tr_b16 v[100:101], v124 offset:15488
	ds_read_b64_tr_b16 v[102:103], v124 offset:16768
	s_waitcnt vmcnt(9) lgkmcnt(2)
	v_mfma_f32_32x32x16_bf16 v[0:15], v[96:99], v[92:95], v[0:15]
	s_waitcnt vmcnt(8) lgkmcnt(0)
	v_mfma_f32_32x32x16_bf16 v[0:15], v[100:103], v[88:91], v[0:15]
	v_mfma_f32_32x32x16_bf16 v[16:31], v[100:103], v[92:95], v[16:31]
	v_mfma_f32_32x32x16_bf16 v[32:47], v[96:99], v[88:91], v[32:47]
	ds_read_b64_tr_b16 v[88:89], v124 offset:20480
	ds_read_b64_tr_b16 v[90:91], v124 offset:21760
	ds_read_b64_tr_b16 v[92:93], v124 offset:20608
	ds_read_b64_tr_b16 v[94:95], v124 offset:21888
	s_waitcnt vmcnt(7) lgkmcnt(2)
	v_mfma_f32_32x32x16_bf16 v[0:15], v[88:91], v[84:87], v[0:15]
	s_waitcnt vmcnt(6) lgkmcnt(0)
	v_mfma_f32_32x32x16_bf16 v[0:15], v[92:95], v[80:83], v[0:15]
	v_mfma_f32_32x32x16_bf16 v[16:31], v[92:95], v[84:87], v[16:31]
	v_mfma_f32_32x32x16_bf16 v[32:47], v[88:91], v[80:83], v[32:47]
	ds_read_b64_tr_b16 v[80:81], v124 offset:25600
	ds_read_b64_tr_b16 v[82:83], v124 offset:26880
	ds_read_b64_tr_b16 v[84:85], v124 offset:25728
	ds_read_b64_tr_b16 v[86:87], v124 offset:27008
	s_waitcnt vmcnt(5) lgkmcnt(2)
	v_mfma_f32_32x32x16_bf16 v[0:15], v[80:83], v[76:79], v[0:15]
	s_waitcnt vmcnt(4) lgkmcnt(0)
	v_mfma_f32_32x32x16_bf16 v[0:15], v[84:87], v[72:75], v[0:15]
	v_mfma_f32_32x32x16_bf16 v[16:31], v[84:87], v[76:79], v[16:31]
	v_mfma_f32_32x32x16_bf16 v[32:47], v[80:83], v[72:75], v[32:47]
	ds_read_b64_tr_b16 v[72:73], v124 offset:30720
	ds_read_b64_tr_b16 v[74:75], v124 offset:32000
	ds_read_b64_tr_b16 v[76:77], v124 offset:30848
	ds_read_b64_tr_b16 v[78:79], v124 offset:32128
	s_waitcnt vmcnt(3) lgkmcnt(2)
	v_mfma_f32_32x32x16_bf16 v[0:15], v[72:75], v[68:71], v[0:15]
	s_waitcnt vmcnt(2) lgkmcnt(0)
	v_mfma_f32_32x32x16_bf16 v[0:15], v[76:79], v[64:67], v[0:15]
	v_mfma_f32_32x32x16_bf16 v[16:31], v[76:79], v[68:71], v[16:31]
	v_mfma_f32_32x32x16_bf16 v[32:47], v[72:75], v[64:67], v[32:47]
	ds_read_b64_tr_b16 v[64:65], v124 offset:35840
	ds_read_b64_tr_b16 v[66:67], v124 offset:37120
	ds_read_b64_tr_b16 v[68:69], v124 offset:35968
	ds_read_b64_tr_b16 v[70:71], v124 offset:37248
	s_waitcnt vmcnt(1) lgkmcnt(2)
	v_mfma_f32_32x32x16_bf16 v[0:15], v[64:67], v[60:63], v[0:15]
	s_waitcnt vmcnt(0) lgkmcnt(0)
	v_mfma_f32_32x32x16_bf16 v[0:15], v[68:71], v[56:59], v[0:15]
	v_mfma_f32_32x32x16_bf16 v[32:47], v[64:67], v[56:59], v[32:47]
	v_mul_lo_u32 v56, v107, s34
	v_and_b32_e32 v56, 0x3fff, v56
	v_cvt_f32_u32_e32 v56, v56
	v_mul_f32_e32 v57, 0x38800000, v56
	v_mfma_f32_32x32x16_bf16 v[16:31], v[68:71], v[60:63], v[16:31]
	v_sin_f32_e32 v58, v57
	v_cos_f32_e32 v56, v57
	s_nop 9
	v_sub_f32_e32 v47, v31, v47
	v_sub_f32_e32 v46, v30, v46
	v_sub_f32_e32 v31, v23, v39
	v_sub_f32_e32 v30, v22, v38
	v_sub_f32_e32 v23, v21, v37
	v_sub_f32_e32 v22, v20, v36
	v_sub_f32_e32 v21, v19, v35
	v_sub_f32_e32 v20, v18, v34
	v_sub_f32_e32 v19, v17, v33
	v_sub_f32_e32 v18, v16, v32
	v_pk_mul_f32 v[16:17], v[58:59], v[0:1] op_sel_hi:[0,1]
	v_pk_fma_f32 v[16:17], v[56:57], v[18:19], v[16:17] op_sel_hi:[0,1,1] neg_lo:[0,0,1] neg_hi:[0,0,1]
	v_pk_mul_f32 v[18:19], v[58:59], v[18:19] op_sel_hi:[0,1]
	v_sub_f32_e32 v41, v25, v41
	v_sub_f32_e32 v40, v24, v40
	v_pk_fma_f32 v[24:25], v[56:57], v[0:1], v[18:19] op_sel_hi:[0,1,1]
	v_pk_mul_f32 v[0:1], v[58:59], v[2:3] op_sel_hi:[0,1]
	v_pk_fma_f32 v[18:19], v[56:57], v[20:21], v[0:1] op_sel_hi:[0,1,1] neg_lo:[0,0,1] neg_hi:[0,0,1]
	v_pk_mul_f32 v[0:1], v[58:59], v[20:21] op_sel_hi:[0,1]
	v_sub_f32_e32 v43, v27, v43
	v_sub_f32_e32 v42, v26, v42
	v_pk_fma_f32 v[26:27], v[56:57], v[2:3], v[0:1] op_sel_hi:[0,1,1]
	v_pk_mul_f32 v[0:1], v[58:59], v[4:5] op_sel_hi:[0,1]
	v_pk_fma_f32 v[20:21], v[56:57], v[22:23], v[0:1] op_sel_hi:[0,1,1] neg_lo:[0,0,1] neg_hi:[0,0,1]
	v_pk_mul_f32 v[0:1], v[58:59], v[22:23] op_sel_hi:[0,1]
	v_sub_f32_e32 v45, v29, v45
	v_sub_f32_e32 v44, v28, v44
	v_pk_fma_f32 v[28:29], v[56:57], v[4:5], v[0:1] op_sel_hi:[0,1,1]
	v_pk_mul_f32 v[0:1], v[58:59], v[6:7] op_sel_hi:[0,1]
	v_pk_fma_f32 v[22:23], v[56:57], v[30:31], v[0:1] op_sel_hi:[0,1,1] neg_lo:[0,0,1] neg_hi:[0,0,1]
	v_pk_mul_f32 v[0:1], v[58:59], v[30:31] op_sel_hi:[0,1]
	v_pk_fma_f32 v[30:31], v[56:57], v[6:7], v[0:1] op_sel_hi:[0,1,1]
	v_pk_mul_f32 v[2:3], v[58:59], v[40:41] op_sel_hi:[0,1]
	v_pk_mul_f32 v[4:5], v[58:59], v[42:43] op_sel_hi:[0,1]
	v_pk_mul_f32 v[6:7], v[58:59], v[44:45] op_sel_hi:[0,1]
	v_pk_mul_f32 v[32:33], v[58:59], v[46:47] op_sel_hi:[0,1]
	v_pk_mul_f32 v[0:1], v[58:59], v[8:9] op_sel_hi:[0,1]
	v_pk_fma_f32 v[8:9], v[56:57], v[8:9], v[2:3] op_sel_hi:[0,1,1]
	v_pk_mul_f32 v[2:3], v[58:59], v[10:11] op_sel_hi:[0,1]
	v_pk_fma_f32 v[10:11], v[56:57], v[10:11], v[4:5] op_sel_hi:[0,1,1]
	v_pk_mul_f32 v[4:5], v[58:59], v[12:13] op_sel_hi:[0,1]
	v_pk_fma_f32 v[12:13], v[56:57], v[12:13], v[6:7] op_sel_hi:[0,1,1]
	v_pk_mul_f32 v[6:7], v[58:59], v[14:15] op_sel_hi:[0,1]
	v_pk_fma_f32 v[14:15], v[56:57], v[14:15], v[32:33] op_sel_hi:[0,1,1]
	v_lshl_add_u32 v32, v107, 7, s23
	v_ashrrev_i32_e32 v33, 31, v32
	v_add_u32_e32 v34, s22, v106
	v_lshlrev_b64 v[32:33], 11, v[32:33]
	v_lshl_add_u64 v[32:33], s[10:11], 0, v[32:33]
	v_ashrrev_i32_e32 v35, 31, v34
	v_lshl_add_u64 v[32:33], v[34:35], 1, v[32:33]
	v_cvt_pk_bf16_f32 v8, v8, v9
	v_cvt_pk_bf16_f32 v9, v10, v11
	v_cvt_pk_bf16_f32 v10, v12, v13
	v_cvt_pk_bf16_f32 v11, v14, v15
	v_pk_fma_f32 v[0:1], v[56:57], v[40:41], v[0:1] op_sel_hi:[0,1,1] neg_lo:[0,0,1] neg_hi:[0,0,1]
	v_pk_fma_f32 v[2:3], v[56:57], v[42:43], v[2:3] op_sel_hi:[0,1,1] neg_lo:[0,0,1] neg_hi:[0,0,1]
	v_pk_fma_f32 v[4:5], v[56:57], v[44:45], v[4:5] op_sel_hi:[0,1,1] neg_lo:[0,0,1] neg_hi:[0,0,1]
	v_pk_fma_f32 v[6:7], v[56:57], v[46:47], v[6:7] op_sel_hi:[0,1,1] neg_lo:[0,0,1] neg_hi:[0,0,1]
	v_lshl_add_u64 v[32:33], v[32:33], 0, v[104:105]
	v_permlane32_swap_b32_e32 v8, v10
	v_permlane32_swap_b32_e32 v9, v11
	v_cvt_pk_bf16_f32 v24, v24, v25
	v_cvt_pk_bf16_f32 v25, v26, v27
	v_cvt_pk_bf16_f32 v26, v28, v29
	v_cvt_pk_bf16_f32 v27, v30, v31
	global_store_dwordx4 v[32:33], v[8:11], off offset:32
	v_cvt_pk_bf16_f32 v0, v0, v1
	v_cvt_pk_bf16_f32 v1, v2, v3
	v_cvt_pk_bf16_f32 v8, v16, v17
	v_cvt_pk_bf16_f32 v9, v18, v19
	v_cvt_pk_bf16_f32 v10, v20, v21
	v_cvt_pk_bf16_f32 v11, v22, v23
	v_cvt_pk_bf16_f32 v2, v4, v5
	v_cvt_pk_bf16_f32 v3, v6, v7
	v_permlane32_swap_b32_e32 v24, v26
	v_permlane32_swap_b32_e32 v25, v27
	v_permlane32_swap_b32_e32 v8, v10
	v_permlane32_swap_b32_e32 v9, v11
	v_permlane32_swap_b32_e32 v0, v2
	v_permlane32_swap_b32_e32 v1, v3
	global_store_dwordx4 v[32:33], v[24:27], off
	global_store_dwordx4 v[32:33], v[8:11], off offset:1024
	global_store_dwordx4 v[32:33], v[0:3], off offset:1056
	s_barrier
	s_branch .LBB0_432

; __device__ __forceinline__ int opaque_tid() { int t = threadIdx.x; asm volatile("" : "+v"(t)); return t; }
; __device__ __forceinline__ float bf_lo(unsigned u) { return __uint_as_float(u << 16); }
; __device__ __forceinline__ float bf_hi(unsigned u) { return __uint_as_float(u & 0xffff0000u); }
; __global__ void __launch_bounds__(512, 2) mega(Params p) {
;     ...
;   const int tidf = opaque_tid(), wvf = tidf >> 6, lanef = tidf & 63;
;   for (int r = blockIdx.x * 8 + wvf; r < T_TOK; r += G * 8) {
;     const float rs = row_rstd(RSS, r);
; #pragma unroll
;     for (int k = 0; k < 4; ++k) { const size_t o = (size_t)r * DM + k * 256 + lanef * 4; const f32x4 g = *(const f32x4*)(p.in[22] + k * 256 + lanef * 4);
;       const u32x2 hi = *(const u32x2*)(XB + o);
;       f32x4 v = {bf_lo(hi[0]), bf_hi(hi[0]), bf_lo(hi[1]), bf_hi(hi[1])};
;       *(f32x4*)(X + o) = v * rs * g; }
;   }
.LBB0_1286:
	v_readlane_b32 s0, v250, 16
	v_ashrrev_i32_e32 v0, 6, v214
	s_nop 0
	v_add_u32_e32 v0, s0, v0
	s_mov_b32 s0, 0x8000
	v_cmp_gt_i32_e32 vcc, s0, v0
	s_and_saveexec_b64 s[0:1], vcc
	v_readlane_b32 s16, v255, 42
	v_readlane_b32 s17, v255, 43
	s_cbranch_execz .LBB0_1289
	v_lshlrev_b32_e32 v1, 4, v214
	v_and_b32_e32 v2, 0x3f0, v1
	v_ashrrev_i32_e32 v1, 31, v0
	v_readlane_b32 s0, v250, 33
	v_and_b32_e32 v10, 63, v214
	v_lshlrev_b64 v[8:9], 12, v[0:1]
	v_readlane_b32 s1, v250, 34
	v_readlane_b32 s14, v250, 47
	v_readlane_b32 s15, v250, 48
	v_lshl_or_b32 v8, v10, 4, v8
	v_mov_b32_e32 v3, 0
	v_readlane_b32 s2, v250, 35
	v_readlane_b32 s3, v250, 36
	v_readlane_b32 s4, v250, 37
	v_readlane_b32 s5, v250, 38
	v_readlane_b32 s6, v250, 39
	v_readlane_b32 s7, v250, 40
	v_readlane_b32 s8, v250, 41
	v_readlane_b32 s9, v250, 42
	v_readlane_b32 s10, v250, 43
	v_readlane_b32 s11, v250, 44
	v_readlane_b32 s12, v250, 45
	v_readlane_b32 s13, v250, 46
	v_lshlrev_b64 v[4:5], 11, v[0:1]
	s_ashr_i32 s17, s16, 31
	v_lshl_add_u64 v[8:9], s[14:15], 0, v[8:9]
	s_mov_b64 s[0:1], 0x800
	v_lshl_add_u64 v[2:3], s[12:13], 0, v[2:3]
	v_lshl_or_b32 v4, v10, 3, v4
	s_lshl_b64 s[2:3], s[16:17], 11
	v_lshlrev_b64 v[6:7], 6, v[0:1]
	s_lshl_b64 s[4:5], s[16:17], 6
	v_lshl_add_u64 v[8:9], v[8:9], 0, s[0:1]
	s_lshl_b64 s[6:7], s[16:17], 12
	s_mov_b64 s[8:9], 0
	s_mov_b64 s[10:11], 0xcc0000
	v_mov_b32_e32 v1, 0x358637bd
	s_mov_b32 s12, 0x800000
	s_mov_b32 s13, 0xec0000
	s_movk_i32 s14, 0x7fff
	global_load_dwordx4 v[40:43], v[2:3], off
	global_load_dwordx4 v[44:47], v[2:3], off offset:1024
	global_load_dwordx4 v[48:51], v[2:3], off offset:2048
	global_load_dwordx4 v[52:55], v[2:3], off offset:3072
	s_waitcnt vmcnt(0)
.LBB0_1288:
	v_lshl_add_u64 v[18:19], s[88:89], 0, v[6:7]
	v_lshl_add_u64 v[10:11], s[88:89], 0, v[4:5]
	v_lshl_add_u64 v[30:31], v[18:19], 0, s[10:11]
	v_add_co_u32_e64 v34, s[0:1], s13, v10
	s_nop 1
	v_addc_co_u32_e64 v35, s[0:1], 0, v11, s[0:1]
	global_load_dwordx4 v[10:13], v[30:31], off offset:16
	global_load_dwordx4 v[14:17], v[30:31], off offset:32
	global_load_dwordx2 v[36:37], v[34:35], off
	global_load_dwordx4 v[18:21], v[30:31], off
	global_load_dwordx4 v[22:25], v[30:31], off offset:48
	global_load_dwordx2 v[56:57], v[34:35], off offset:512
	global_load_dwordx2 v[58:59], v[34:35], off offset:1024
	global_load_dwordx2 v[60:61], v[34:35], off offset:1536
	v_add_u32_e32 v0, s16, v0
	v_lshl_add_u64 v[4:5], v[4:5], 0, s[2:3]
	v_lshl_add_u64 v[6:7], v[6:7], 0, s[4:5]
	s_waitcnt vmcnt(7)
	v_mov_b32_e32 v30, v11
	v_mov_b32_e32 v31, v12
	v_mov_b32_e32 v11, v13
	s_waitcnt vmcnt(6)
	v_add_f32_e32 v12, v14, v15
	v_add_f32_e32 v14, v16, v17
	s_waitcnt vmcnt(5)
	v_lshlrev_b32_e32 v16, 16, v36
	v_and_b32_e32 v17, 0xffff0000, v36
	v_lshlrev_b32_e32 v32, 16, v37
	v_and_b32_e32 v33, 0xffff0000, v37
	s_waitcnt vmcnt(4)
	v_mov_b32_e32 v36, v19
	v_mov_b32_e32 v37, v20
	v_mov_b32_e32 v19, v21
	v_pk_add_f32 v[10:11], v[30:31], v[10:11]
	s_waitcnt vmcnt(3)
	v_mov_b32_e32 v13, v24
	v_mov_b32_e32 v15, v25
	v_pk_add_f32 v[18:19], v[36:37], v[18:19]
	v_pk_add_f32 v[10:11], v[10:11], v[10:11] op_sel:[0,1] op_sel_hi:[1,0]
	v_pk_add_f32 v[12:13], v[12:13], v[14:15]
	v_pk_add_f32 v[14:15], v[18:19], v[18:19] op_sel:[0,1] op_sel_hi:[1,0]
	v_mov_b32_e32 v11, v23
	v_mov_b32_e32 v15, v22
	v_pk_add_f32 v[10:11], v[14:15], v[10:11]
	s_nop 0
	v_pk_add_f32 v[10:11], v[10:11], v[12:13]
	s_nop 0
	v_add_f32_e32 v10, v10, v11
	v_fmamk_f32 v10, v10, 0x3a800000, v1
	v_mul_f32_e32 v11, 0x4b800000, v10
	v_cmp_gt_f32_e32 vcc, s12, v10
	s_nop 1
	v_cndmask_b32_e32 v10, v10, v11, vcc
	v_rsq_f32_e32 v10, v10
	s_nop 0
	v_mul_f32_e32 v11, 0x45800000, v10
	v_cndmask_b32_e32 v14, v10, v11, vcc
	v_pk_mul_f32 v[10:11], v[14:15], v[16:17] op_sel_hi:[0,1]
	v_pk_mul_f32 v[12:13], v[14:15], v[32:33] op_sel_hi:[0,1]
	v_pk_mul_f32 v[12:13], v[42:43], v[12:13]
	v_pk_mul_f32 v[10:11], v[40:41], v[10:11]
	global_store_dwordx4 v[8:9], v[10:13], off offset:-2048
	v_cmp_lt_i32_e32 vcc, s14, v0
	s_or_b64 s[8:9], vcc, s[8:9]
	s_waitcnt vmcnt(3)
	v_lshlrev_b32_e32 v18, 16, v56
	v_and_b32_e32 v19, 0xffff0000, v56
	v_lshlrev_b32_e32 v16, 16, v57
	v_and_b32_e32 v17, 0xffff0000, v57
	v_pk_mul_f32 v[18:19], v[14:15], v[18:19] op_sel_hi:[0,1]
	v_pk_mul_f32 v[16:17], v[14:15], v[16:17] op_sel_hi:[0,1]
	v_pk_mul_f32 v[64:65], v[46:47], v[16:17]
	v_pk_mul_f32 v[62:63], v[44:45], v[18:19]
	global_store_dwordx4 v[8:9], v[62:65], off offset:-1024
	s_waitcnt vmcnt(3)
	v_lshlrev_b32_e32 v18, 16, v58
	v_and_b32_e32 v19, 0xffff0000, v58
	v_lshlrev_b32_e32 v16, 16, v59
	v_and_b32_e32 v17, 0xffff0000, v59
	v_pk_mul_f32 v[18:19], v[14:15], v[18:19] op_sel_hi:[0,1]
	v_pk_mul_f32 v[16:17], v[14:15], v[16:17] op_sel_hi:[0,1]
	v_pk_mul_f32 v[68:69], v[50:51], v[16:17]
	v_pk_mul_f32 v[66:67], v[48:49], v[18:19]
	global_store_dwordx4 v[8:9], v[66:69], off
	s_waitcnt vmcnt(3)
	v_lshlrev_b32_e32 v18, 16, v60
	v_and_b32_e32 v19, 0xffff0000, v60
	v_lshlrev_b32_e32 v16, 16, v61
	v_and_b32_e32 v17, 0xffff0000, v61
	v_pk_mul_f32 v[18:19], v[14:15], v[18:19] op_sel_hi:[0,1]
	v_pk_mul_f32 v[16:17], v[14:15], v[16:17] op_sel_hi:[0,1]
	v_pk_mul_f32 v[72:73], v[54:55], v[16:17]
	v_pk_mul_f32 v[70:71], v[52:53], v[18:19]
	global_store_dwordx4 v[8:9], v[70:73], off offset:1024
	v_lshl_add_u64 v[8:9], v[8:9], 0, s[6:7]
	s_andn2_b64 exec, exec, s[8:9]
	s_cbranch_execnz .LBB0_1288
